# v46: v45 + duplicate s_waitcnt lgkmcnt(0) after the MFMA-section barriers removed in both GEMM K-loops
# baseline (speedup 1.0000x reference)
; #define G_STAGE(bufoff, gbase, voff) do { _Pragma("unroll") for (int _i = 0; _i < 2; ++_i) \
;     __builtin_amdgcn_global_load_lds((const unsigned*)((const char*)(gbase) + (voff)[_i]), (LAS unsigned*)(lds + (bufoff) + ldsw + _i * 8192), 16, 0, 0); } while (0)
; #define G_LDA(dst, b, h) do { _Pragma("unroll") for (int m = 0; m < 4; ++m) _Pragma("unroll") for (int k = 0; k < 2; ++k) dst[m][k] = *(const LAS bf16x8*)(lds + G_SA(b, h) + aoff + m * 2048 + k * 1024); } while (0)
; #define G_LDB(dst, b, h) do { _Pragma("unroll") for (int n = 0; n < 2; ++n) _Pragma("unroll") for (int k = 0; k < 2; ++k) dst[n][k] = *(const LAS bf16x8*)(lds + G_SB(b, h) + boff + n * 2048 + k * 1024); } while (0)
; #define G_WAIT_V(n) asm volatile("s_waitcnt vmcnt(" #n ")" ::: "memory")
; template <int GP> DI void gemm_phase(const Params& p, int l, int which, char* smem, int wv) {
;     ...
;     const int ntn = next_unit(ct, nmt, nnt, nk0, nnk);
;     const bool has_next = ntn >= 0;
;     const char* nA = has_next ? (const char*)Aglob + (size_t)nmt * tstep + (size_t)nk0 * 2 : cA;
;     const char* nB = has_next ? (const char*)Wt + (size_t)nnt * tstep + (size_t)nk0 * 2 : cB;
;     const bool n32 = has_next ? ((!which) && (nnt < 4)) : c32;
;     for (int t = 0; t < cnk; t += 2) {
;       const bool last = (t == cnk - 2);
;       const char* a1 = cA + (size_t)(t + 1) * kstep;
;       const char* a2 = last ? nA : cA + (size_t)(t + 2) * kstep; const char* b2 = last ? nB : cB + (size_t)(t + 2) * kstep;
;       const char* a3 = a2 + kstep; const char* b3 = b2 + kstep;
;       if (last) {
; #pragma unroll
;         for (int i = 0; i < 2; ++i) { vb0[i] = voffB(i, 0, n32); vb1[i] = voffB(i, 1, n32); }
;       }
;       G_LDB(B0, 0, 0); G_SCHED; G_LDA(At, 0, 0); G_STAGE(G_SA(1, 1), a1 + hstep, voffA);
;       G_WAIT_L(8); G_BAR; G_WAIT_L(0); G_MMA(0, 0, At, B0); G_BAR; G_SCHED;
;       G_LDB(B1, 0, 1); G_STAGE(G_SB(0, 0), b2, vb0);
;       G_BAR; G_WAIT_L(0); G_MMA(0, 1, At, B1); G_BAR;
;       G_LDA(At, 0, 1); G_STAGE(G_SA(0, 0), a2, voffA);
;       G_BAR; G_WAIT_L(0); G_MMA(1, 0, At, B0); G_BAR; G_SCHED;
;       G_STAGE(G_SB(0, 1), b2, vb1);
;       G_WAIT_V(6); G_BAR; G_MMA(1, 1, At, B1); G_BAR;
;       G_LDB(B0, 1, 0); G_SCHED; G_LDA(At, 1, 0); G_STAGE(G_SA(0, 1), a2 + hstep, voffA);
;       G_WAIT_L(8); G_BAR; G_WAIT_L(0); G_MMA(0, 0, At, B0); G_BAR; G_SCHED;
.LBB0_149:
	v_add_u32_e32 v135, 0x10000, v166
	s_add_u32 s61, s8, s26
	ds_read_b128 v[168:171], v135
	ds_read_b128 v[172:175], v135 offset:1024
	ds_read_b128 v[176:179], v135 offset:2048
	ds_read_b128 v[180:183], v135 offset:3072
	s_addc_u32 s62, s9, s27
	s_and_b64 s[30:31], s[28:29], exec
	s_cselect_b32 s31, s11, s62
	s_cselect_b32 s30, s57, s61
	s_add_u32 s61, s6, s26
	s_addc_u32 s62, s7, s27
	s_and_b64 s[28:29], s[28:29], exec
	s_cselect_b32 s28, s59, s61
	s_cselect_b32 s29, s58, s62
	s_mov_b32 m0, s53
	v_lshl_add_u64 v[216:217], s[8:9], 0, v[162:163]
	ds_read_b128 v[184:187], v165
	ds_read_b128 v[188:191], v165 offset:1024
	ds_read_b128 v[192:195], v165 offset:2048
	ds_read_b128 v[196:199], v165 offset:3072
	ds_read_b128 v[200:203], v165 offset:4096
	ds_read_b128 v[204:207], v165 offset:5120
	ds_read_b128 v[208:211], v165 offset:6144
	ds_read_b128 v[212:215], v165 offset:7168
	global_load_lds_dwordx4 v[216:217], off
	v_lshl_add_u64 v[216:217], s[8:9], 0, v[160:161]
	s_mov_b32 m0, s54
	s_nop 0
	global_load_lds_dwordx4 v[216:217], off
	s_waitcnt lgkmcnt(8)
	s_barrier
	s_waitcnt lgkmcnt(0)
	v_mfma_f32_16x16x32_bf16 v[62:65], v[168:171], v[184:187], v[62:65]
	v_mfma_f32_16x16x32_bf16 v[58:61], v[176:179], v[184:187], v[58:61]
	v_mfma_f32_16x16x32_bf16 v[54:57], v[168:171], v[192:195], v[54:57]
	v_mfma_f32_16x16x32_bf16 v[50:53], v[176:179], v[192:195], v[50:53]
	v_mfma_f32_16x16x32_bf16 v[46:49], v[168:171], v[200:203], v[46:49]
	v_mfma_f32_16x16x32_bf16 v[42:45], v[176:179], v[200:203], v[42:45]
	v_mfma_f32_16x16x32_bf16 v[38:41], v[168:171], v[208:211], v[38:41]
	v_mfma_f32_16x16x32_bf16 v[34:37], v[176:179], v[208:211], v[34:37]
	v_mfma_f32_16x16x32_bf16 v[62:65], v[172:175], v[188:191], v[62:65]
	v_mfma_f32_16x16x32_bf16 v[58:61], v[180:183], v[188:191], v[58:61]
	v_mfma_f32_16x16x32_bf16 v[54:57], v[172:175], v[196:199], v[54:57]
	v_mfma_f32_16x16x32_bf16 v[50:53], v[180:183], v[196:199], v[50:53]
	v_mfma_f32_16x16x32_bf16 v[46:49], v[172:175], v[204:207], v[46:49]
	v_mfma_f32_16x16x32_bf16 v[42:45], v[180:183], v[204:207], v[42:45]
	v_mfma_f32_16x16x32_bf16 v[38:41], v[172:175], v[212:215], v[38:41]
	v_mfma_f32_16x16x32_bf16 v[34:37], v[180:183], v[212:215], v[34:37]
	s_barrier
	s_mov_b32 m0, s1
	v_add_u32_e32 v135, 0x14000, v166
	ds_read_b128 v[216:219], v135
	ds_read_b128 v[220:223], v135 offset:1024
	ds_read_b128 v[224:227], v135 offset:2048
	ds_read_b128 v[238:241], v135 offset:3072
	global_load_lds_dwordx4 v0, s[28:29]
	s_mov_b32 m0, s3
	v_mov_b32_e32 v137, v1
	global_load_lds_dwordx4 v136, s[28:29]
	s_barrier
	s_waitcnt lgkmcnt(0)
	v_lshl_add_u64 v[228:229], s[28:29], 0, v[0:1]
	v_lshl_add_u64 v[234:235], s[28:29], 0, v[136:137]
	s_waitcnt lgkmcnt(0)
	v_mfma_f32_16x16x32_bf16 v[30:33], v[216:219], v[184:187], v[30:33]
	v_mfma_f32_16x16x32_bf16 v[26:29], v[224:227], v[184:187], v[26:29]
	v_mfma_f32_16x16x32_bf16 v[22:25], v[216:219], v[192:195], v[22:25]
	v_mfma_f32_16x16x32_bf16 v[18:21], v[224:227], v[192:195], v[18:21]
	v_mfma_f32_16x16x32_bf16 v[14:17], v[216:219], v[200:203], v[14:17]
	v_mfma_f32_16x16x32_bf16 v[10:13], v[224:227], v[200:203], v[10:13]
	v_mfma_f32_16x16x32_bf16 v[6:9], v[216:219], v[208:211], v[6:9]
	v_mfma_f32_16x16x32_bf16 v[2:5], v[224:227], v[208:211], v[2:5]
	v_mfma_f32_16x16x32_bf16 v[30:33], v[220:223], v[188:191], v[30:33]
	v_mfma_f32_16x16x32_bf16 v[26:29], v[238:241], v[188:191], v[26:29]
	v_mfma_f32_16x16x32_bf16 v[22:25], v[220:223], v[196:199], v[22:25]
	v_mfma_f32_16x16x32_bf16 v[18:21], v[238:241], v[196:199], v[18:21]
	v_mfma_f32_16x16x32_bf16 v[14:17], v[220:223], v[204:207], v[14:17]
	v_mfma_f32_16x16x32_bf16 v[10:13], v[238:241], v[204:207], v[10:13]
	v_mfma_f32_16x16x32_bf16 v[6:9], v[220:223], v[212:215], v[6:9]
	v_mfma_f32_16x16x32_bf16 v[2:5], v[238:241], v[212:215], v[2:5]
	s_mov_b32 m0, s38
	v_lshl_add_u64 v[242:243], s[30:31], 0, v[130:131]
	s_barrier
	ds_read_b128 v[184:187], v165 offset:16384
	ds_read_b128 v[188:191], v165 offset:17408
	ds_read_b128 v[192:195], v165 offset:18432
	ds_read_b128 v[196:199], v165 offset:19456
	ds_read_b128 v[200:203], v165 offset:20480
	ds_read_b128 v[204:207], v165 offset:21504
	ds_read_b128 v[208:211], v165 offset:22528
	ds_read_b128 v[212:215], v165 offset:23552
	global_load_lds_dwordx4 v[242:243], off
	v_lshl_add_u64 v[244:245], s[30:31], 0, v[132:133]
	s_mov_b32 m0, s5
	s_nop 0
	global_load_lds_dwordx4 v[244:245], off
	s_barrier
	s_waitcnt lgkmcnt(0)
	v_mfma_f32_16x16x32_bf16 v[66:69], v[168:171], v[184:187], v[66:69]
	v_mfma_f32_16x16x32_bf16 v[70:73], v[176:179], v[184:187], v[70:73]
	v_mfma_f32_16x16x32_bf16 v[74:77], v[168:171], v[192:195], v[74:77]
	v_mfma_f32_16x16x32_bf16 v[78:81], v[176:179], v[192:195], v[78:81]
	v_mfma_f32_16x16x32_bf16 v[82:85], v[168:171], v[200:203], v[82:85]
	v_mfma_f32_16x16x32_bf16 v[86:89], v[176:179], v[200:203], v[86:89]
	v_mfma_f32_16x16x32_bf16 v[90:93], v[168:171], v[208:211], v[90:93]
	v_mfma_f32_16x16x32_bf16 v[98:101], v[176:179], v[208:211], v[98:101]
	v_mfma_f32_16x16x32_bf16 v[66:69], v[172:175], v[188:191], v[66:69]
	v_mfma_f32_16x16x32_bf16 v[70:73], v[180:183], v[188:191], v[70:73]
	v_mfma_f32_16x16x32_bf16 v[74:77], v[172:175], v[196:199], v[74:77]
	v_mfma_f32_16x16x32_bf16 v[78:81], v[180:183], v[196:199], v[78:81]
	v_mfma_f32_16x16x32_bf16 v[82:85], v[172:175], v[204:207], v[82:85]
	v_mfma_f32_16x16x32_bf16 v[86:89], v[180:183], v[204:207], v[86:89]
	v_mfma_f32_16x16x32_bf16 v[90:93], v[172:175], v[212:215], v[90:93]
	v_mfma_f32_16x16x32_bf16 v[98:101], v[180:183], v[212:215], v[98:101]
	s_barrier
; #define G_STAGE(bufoff, gbase, voff) do { _Pragma("unroll") for (int _i = 0; _i < 2; ++_i) \
;     __builtin_amdgcn_global_load_lds((const unsigned*)((const char*)(gbase) + (voff)[_i]), (LAS unsigned*)(lds + (bufoff) + ldsw + _i * 8192), 16, 0, 0); } while (0)
; #define G_LDA(dst, b, h) do { _Pragma("unroll") for (int m = 0; m < 4; ++m) _Pragma("unroll") for (int k = 0; k < 2; ++k) dst[m][k] = *(const LAS bf16x8*)(lds + G_SA(b, h) + aoff + m * 2048 + k * 1024); } while (0)
; #define G_LDB(dst, b, h) do { _Pragma("unroll") for (int n = 0; n < 2; ++n) _Pragma("unroll") for (int k = 0; k < 2; ++k) dst[n][k] = *(const LAS bf16x8*)(lds + G_SB(b, h) + boff + n * 2048 + k * 1024); } while (0)
; #define G_MMA(ai, bj, At, Bt) do { __builtin_amdgcn_s_setprio(1); _Pragma("unroll") for (int m = 0; m < 4; ++m) _Pragma("unroll") for (int n = 0; n < 2; ++n) _Pragma("unroll") for (int k = 0; k < 2; ++k) \
;     acc[ai][bj][m][n] = __builtin_amdgcn_mfma_f32_16x16x32_bf16(Bt[n][k], At[m][k], acc[ai][bj][m][n], 0, 0, 0); __builtin_amdgcn_s_setprio(0); } while (0)
; #define G_WAIT_V(n) asm volatile("s_waitcnt vmcnt(" #n ")" ::: "memory")
; #define G_WAIT_L(n) asm volatile("s_waitcnt lgkmcnt(" #n ")" ::: "memory")
; #define G_BAR __builtin_amdgcn_s_barrier()
; #define G_SCHED __builtin_amdgcn_sched_barrier(0)
; template <int GP> DI void gemm_phase(const Params& p, int l, int which, char* smem, int wv) {
;     ...
;       G_WAIT_V(6); G_BAR; G_MMA(1, 1, At, B1); G_BAR;
;       G_LDB(B0, 1, 0); G_SCHED; G_LDA(At, 1, 0); G_STAGE(G_SA(0, 1), a2 + hstep, voffA);
;       G_WAIT_L(8); G_BAR; G_WAIT_L(0); G_MMA(0, 0, At, B0); G_BAR; G_SCHED;
;       G_LDB(B1, 1, 1); G_STAGE(G_SB(1, 0), b3, vb0);
;       G_BAR; G_WAIT_L(0); G_MMA(0, 1, At, B1); G_BAR;
;       G_LDA(At, 1, 1); G_STAGE(G_SA(1, 0), a3, voffA);
	s_mov_b32 m0, s41
	v_mov_b32_e32 v135, v1
	global_load_lds_dwordx4 v134, s[28:29]
	s_mov_b32 m0, s42
	v_mov_b32_e32 v155, v1
	global_load_lds_dwordx4 v154, s[28:29]
	s_waitcnt vmcnt(6)
	v_lshl_add_u64 v[246:247], s[28:29], 0, v[134:135]
	v_lshl_add_u64 v[248:249], s[28:29], 0, v[154:155]
	s_barrier
	v_mfma_f32_16x16x32_bf16 v[94:97], v[216:219], v[184:187], v[94:97]
	v_mfma_f32_16x16x32_bf16 v[102:105], v[224:227], v[184:187], v[102:105]
	v_mfma_f32_16x16x32_bf16 v[106:109], v[216:219], v[192:195], v[106:109]
	v_mfma_f32_16x16x32_bf16 v[110:113], v[224:227], v[192:195], v[110:113]
	v_mfma_f32_16x16x32_bf16 v[114:117], v[216:219], v[200:203], v[114:117]
	v_mfma_f32_16x16x32_bf16 v[118:121], v[224:227], v[200:203], v[118:121]
	v_mfma_f32_16x16x32_bf16 v[122:125], v[216:219], v[208:211], v[122:125]
	v_mfma_f32_16x16x32_bf16 v[126:129], v[224:227], v[208:211], v[126:129]
	v_mfma_f32_16x16x32_bf16 v[94:97], v[220:223], v[188:191], v[94:97]
	v_mfma_f32_16x16x32_bf16 v[102:105], v[238:241], v[188:191], v[102:105]
	v_mfma_f32_16x16x32_bf16 v[106:109], v[220:223], v[196:199], v[106:109]
	v_mfma_f32_16x16x32_bf16 v[110:113], v[238:241], v[196:199], v[110:113]
	v_mfma_f32_16x16x32_bf16 v[114:117], v[220:223], v[204:207], v[114:117]
	v_mfma_f32_16x16x32_bf16 v[118:121], v[238:241], v[204:207], v[118:121]
	v_mfma_f32_16x16x32_bf16 v[122:125], v[220:223], v[212:215], v[122:125]
	v_mfma_f32_16x16x32_bf16 v[126:129], v[238:241], v[212:215], v[126:129]
	v_add_u32_e32 v135, 0x18000, v166
	s_barrier
	ds_read_b128 v[168:171], v135
	ds_read_b128 v[172:175], v135 offset:1024
	ds_read_b128 v[176:179], v135 offset:2048
	ds_read_b128 v[180:183], v135 offset:3072
	s_add_u32 s28, s30, 0x80000
	s_addc_u32 s29, s31, 0
	s_mov_b32 m0, s43
	v_lshl_add_u64 v[216:217], s[28:29], 0, v[130:131]
	ds_read_b128 v[184:187], v165 offset:32768
	ds_read_b128 v[188:191], v165 offset:33792
	ds_read_b128 v[192:195], v165 offset:34816
	ds_read_b128 v[196:199], v165 offset:35840
	ds_read_b128 v[200:203], v165 offset:36864
	ds_read_b128 v[204:207], v165 offset:37888
	ds_read_b128 v[208:211], v165 offset:38912
	ds_read_b128 v[212:215], v165 offset:39936
	global_load_lds_dwordx4 v[216:217], off
	v_lshl_add_u64 v[216:217], s[28:29], 0, v[132:133]
	s_mov_b32 m0, s44
	s_nop 0
	global_load_lds_dwordx4 v[216:217], off
	s_waitcnt lgkmcnt(8)
	s_barrier
	s_waitcnt lgkmcnt(0)
	v_mfma_f32_16x16x32_bf16 v[62:65], v[168:171], v[184:187], v[62:65]
	v_mfma_f32_16x16x32_bf16 v[58:61], v[176:179], v[184:187], v[58:61]
	v_mfma_f32_16x16x32_bf16 v[54:57], v[168:171], v[192:195], v[54:57]
	v_mfma_f32_16x16x32_bf16 v[50:53], v[176:179], v[192:195], v[50:53]
	v_mfma_f32_16x16x32_bf16 v[46:49], v[168:171], v[200:203], v[46:49]
	v_mfma_f32_16x16x32_bf16 v[42:45], v[176:179], v[200:203], v[42:45]
	v_mfma_f32_16x16x32_bf16 v[38:41], v[168:171], v[208:211], v[38:41]
	v_mfma_f32_16x16x32_bf16 v[34:37], v[176:179], v[208:211], v[34:37]
	v_mfma_f32_16x16x32_bf16 v[62:65], v[172:175], v[188:191], v[62:65]
	v_mfma_f32_16x16x32_bf16 v[58:61], v[180:183], v[188:191], v[58:61]
	v_mfma_f32_16x16x32_bf16 v[54:57], v[172:175], v[196:199], v[54:57]
	v_mfma_f32_16x16x32_bf16 v[50:53], v[180:183], v[196:199], v[50:53]
	v_mfma_f32_16x16x32_bf16 v[46:49], v[172:175], v[204:207], v[46:49]
	v_mfma_f32_16x16x32_bf16 v[42:45], v[180:183], v[204:207], v[42:45]
	v_mfma_f32_16x16x32_bf16 v[38:41], v[172:175], v[212:215], v[38:41]
	v_mfma_f32_16x16x32_bf16 v[34:37], v[180:183], v[212:215], v[34:37]
	s_barrier
	s_mov_b32 m0, s45
	v_add_u32_e32 v135, 0x1c000, v166
	v_lshl_add_u64 v[228:229], v[228:229], 0, s[74:75]
	ds_read_b128 v[216:219], v135
	ds_read_b128 v[220:223], v135 offset:1024
	ds_read_b128 v[224:227], v135 offset:2048
	ds_read_b128 v[238:241], v135 offset:3072
	global_load_lds_dwordx4 v[228:229], off
	v_lshl_add_u64 v[228:229], v[234:235], 0, s[74:75]
	s_mov_b32 m0, s46
	s_nop 0
	global_load_lds_dwordx4 v[228:229], off
	s_barrier
; #define G_STAGE(bufoff, gbase, voff) do { _Pragma("unroll") for (int _i = 0; _i < 2; ++_i) \
;     __builtin_amdgcn_global_load_lds((const unsigned*)((const char*)(gbase) + (voff)[_i]), (LAS unsigned*)(lds + (bufoff) + ldsw + _i * 8192), 16, 0, 0); } while (0)
; #define G_LDA(dst, b, h) do { _Pragma("unroll") for (int m = 0; m < 4; ++m) _Pragma("unroll") for (int k = 0; k < 2; ++k) dst[m][k] = *(const LAS bf16x8*)(lds + G_SA(b, h) + aoff + m * 2048 + k * 1024); } while (0)
; #define G_MMA(ai, bj, At, Bt) do { __builtin_amdgcn_s_setprio(1); _Pragma("unroll") for (int m = 0; m < 4; ++m) _Pragma("unroll") for (int n = 0; n < 2; ++n) _Pragma("unroll") for (int k = 0; k < 2; ++k) \
;     acc[ai][bj][m][n] = __builtin_amdgcn_mfma_f32_16x16x32_bf16(Bt[n][k], At[m][k], acc[ai][bj][m][n], 0, 0, 0); __builtin_amdgcn_s_setprio(0); } while (0)
; #define G_WAIT_V(n) asm volatile("s_waitcnt vmcnt(" #n ")" ::: "memory")
; #define G_WAIT_L(n) asm volatile("s_waitcnt lgkmcnt(" #n ")" ::: "memory")
; #define G_BAR __builtin_amdgcn_s_barrier()
; #define G_SCHED __builtin_amdgcn_sched_barrier(0)
; template <int GP> DI void gemm_phase(const Params& p, int l, int which, char* smem, int wv) {
;     ...
;       G_LDA(At, 1, 1); G_STAGE(G_SA(1, 0), a3, voffA);
;       G_BAR; G_WAIT_L(0); G_MMA(1, 0, At, B0); G_BAR; G_SCHED;
;       G_STAGE(G_SB(1, 1), b3, vb1);
;       G_WAIT_V(6); G_BAR; G_MMA(1, 1, At, B1); G_BAR;
;     }
;     if (GP == 0) {
;       const int m0 = cmt * 256, n0 = cnt_ * 256;
;       const bool isctx = (cmt % 9) == 0;
;       const int head = wc >> 1;
;       const int n128 = cnt_ * 2 + head;
;       const int rowl0 = wr * 64 + fr;
;       if (which) {
;         const int colb = n0 + head * 128 + (wc & 1) * 32 + fq * 8;
;         u16* ybase = isctx ? p.ypart + ((size_t)(ck0 >> 8) * 1024 + (size_t)(cmt / 9) * 256) * DM : p.y + (size_t)m0 * DM;
	s_waitcnt lgkmcnt(0)
	v_mfma_f32_16x16x32_bf16 v[30:33], v[216:219], v[184:187], v[30:33]
	v_mfma_f32_16x16x32_bf16 v[26:29], v[224:227], v[184:187], v[26:29]
	v_mfma_f32_16x16x32_bf16 v[22:25], v[216:219], v[192:195], v[22:25]
	v_mfma_f32_16x16x32_bf16 v[18:21], v[224:227], v[192:195], v[18:21]
	v_mfma_f32_16x16x32_bf16 v[14:17], v[216:219], v[200:203], v[14:17]
	v_mfma_f32_16x16x32_bf16 v[10:13], v[224:227], v[200:203], v[10:13]
	v_mfma_f32_16x16x32_bf16 v[6:9], v[216:219], v[208:211], v[6:9]
	v_mfma_f32_16x16x32_bf16 v[2:5], v[224:227], v[208:211], v[2:5]
	v_mfma_f32_16x16x32_bf16 v[30:33], v[220:223], v[188:191], v[30:33]
	v_mfma_f32_16x16x32_bf16 v[26:29], v[238:241], v[188:191], v[26:29]
	v_mfma_f32_16x16x32_bf16 v[22:25], v[220:223], v[196:199], v[22:25]
	v_mfma_f32_16x16x32_bf16 v[18:21], v[238:241], v[196:199], v[18:21]
	v_mfma_f32_16x16x32_bf16 v[14:17], v[220:223], v[204:207], v[14:17]
	v_mfma_f32_16x16x32_bf16 v[10:13], v[238:241], v[204:207], v[10:13]
	v_mfma_f32_16x16x32_bf16 v[6:9], v[220:223], v[212:215], v[6:9]
	v_mfma_f32_16x16x32_bf16 v[2:5], v[238:241], v[212:215], v[2:5]
	s_mov_b32 m0, s48
	v_lshl_add_u64 v[228:229], v[242:243], 0, s[74:75]
	s_barrier
	ds_read_b128 v[184:187], v165 offset:49152
	ds_read_b128 v[188:191], v165 offset:50176
	ds_read_b128 v[192:195], v165 offset:51200
	ds_read_b128 v[196:199], v165 offset:52224
	ds_read_b128 v[200:203], v165 offset:53248
	ds_read_b128 v[204:207], v165 offset:54272
	ds_read_b128 v[208:211], v165 offset:55296
	ds_read_b128 v[212:215], v165 offset:56320
	global_load_lds_dwordx4 v[228:229], off
	v_lshl_add_u64 v[228:229], v[244:245], 0, s[74:75]
	s_mov_b32 m0, s49
	s_nop 0
	global_load_lds_dwordx4 v[228:229], off
	s_barrier
	s_waitcnt lgkmcnt(0)
	v_mfma_f32_16x16x32_bf16 v[66:69], v[168:171], v[184:187], v[66:69]
	v_mfma_f32_16x16x32_bf16 v[70:73], v[176:179], v[184:187], v[70:73]
	v_mfma_f32_16x16x32_bf16 v[74:77], v[168:171], v[192:195], v[74:77]
	v_mfma_f32_16x16x32_bf16 v[78:81], v[176:179], v[192:195], v[78:81]
	v_mfma_f32_16x16x32_bf16 v[82:85], v[168:171], v[200:203], v[82:85]
	v_mfma_f32_16x16x32_bf16 v[86:89], v[176:179], v[200:203], v[86:89]
	v_mfma_f32_16x16x32_bf16 v[90:93], v[168:171], v[208:211], v[90:93]
	v_mfma_f32_16x16x32_bf16 v[98:101], v[176:179], v[208:211], v[98:101]
	v_mfma_f32_16x16x32_bf16 v[66:69], v[172:175], v[188:191], v[66:69]
	v_mfma_f32_16x16x32_bf16 v[70:73], v[180:183], v[188:191], v[70:73]
	v_mfma_f32_16x16x32_bf16 v[74:77], v[172:175], v[196:199], v[74:77]
	v_mfma_f32_16x16x32_bf16 v[78:81], v[180:183], v[196:199], v[78:81]
	v_mfma_f32_16x16x32_bf16 v[82:85], v[172:175], v[204:207], v[82:85]
	v_mfma_f32_16x16x32_bf16 v[86:89], v[180:183], v[204:207], v[86:89]
	v_mfma_f32_16x16x32_bf16 v[90:93], v[172:175], v[212:215], v[90:93]
	v_mfma_f32_16x16x32_bf16 v[98:101], v[180:183], v[212:215], v[98:101]
	s_barrier
	s_mov_b32 m0, s50
	v_lshl_add_u64 v[168:169], v[246:247], 0, s[74:75]
	global_load_lds_dwordx4 v[168:169], off
	v_lshl_add_u64 v[168:169], v[248:249], 0, s[74:75]
	s_mov_b32 m0, s52
	s_nop 0
	global_load_lds_dwordx4 v[168:169], off
	s_waitcnt vmcnt(6)
	s_barrier
	v_mfma_f32_16x16x32_bf16 v[94:97], v[216:219], v[184:187], v[94:97]
	v_mfma_f32_16x16x32_bf16 v[102:105], v[224:227], v[184:187], v[102:105]
	v_mfma_f32_16x16x32_bf16 v[106:109], v[216:219], v[192:195], v[106:109]
	v_mfma_f32_16x16x32_bf16 v[110:113], v[224:227], v[192:195], v[110:113]
	v_mfma_f32_16x16x32_bf16 v[114:117], v[216:219], v[200:203], v[114:117]
	v_mfma_f32_16x16x32_bf16 v[118:121], v[224:227], v[200:203], v[118:121]
	v_mfma_f32_16x16x32_bf16 v[122:125], v[216:219], v[208:211], v[122:125]
	v_mfma_f32_16x16x32_bf16 v[126:129], v[224:227], v[208:211], v[126:129]
	v_mfma_f32_16x16x32_bf16 v[94:97], v[220:223], v[188:191], v[94:97]
	v_mfma_f32_16x16x32_bf16 v[102:105], v[238:241], v[188:191], v[102:105]
	v_mfma_f32_16x16x32_bf16 v[106:109], v[220:223], v[196:199], v[106:109]
	v_mfma_f32_16x16x32_bf16 v[110:113], v[238:241], v[196:199], v[110:113]
	v_mfma_f32_16x16x32_bf16 v[114:117], v[220:223], v[204:207], v[114:117]
	v_mfma_f32_16x16x32_bf16 v[118:121], v[238:241], v[204:207], v[118:121]
	v_mfma_f32_16x16x32_bf16 v[122:125], v[220:223], v[212:215], v[122:125]
	v_mfma_f32_16x16x32_bf16 v[126:129], v[238:241], v[212:215], v[126:129]
	s_add_i32 s28, s60, 2
	s_add_u32 s26, s26, 0x100
	s_addc_u32 s27, s27, 0
	v_lshl_add_u64 v[162:163], v[162:163], 0, s[78:79]
	s_cmp_ge_i32 s60, s36
	v_lshl_add_u64 v[160:161], v[160:161], 0, s[78:79]
	s_barrier
	s_cbranch_scc0 .LBB0_147
	s_mul_hi_i32 s11, s2, 0x38e38e39
	s_lshr_b32 s26, s11, 31
	s_ashr_i32 s11, s11, 1
	s_add_i32 s26, s11, s26
	s_mul_i32 s11, s26, 9
	s_sub_i32 s11, s2, s11
	s_cmp_lg_u32 s11, 0
	s_cbranch_scc0 .LBB0_155
	s_lshl_b32 s28, s2, 8
	s_ashr_i32 s29, s28, 31
	s_lshl_b64 s[28:29], s[28:29], 12
	s_add_u32 s28, s94, s28
	s_addc_u32 s29, s95, s29
	s_cbranch_execnz .LBB0_153

; #define G_STAGE(bufoff, gbase, voff) do { _Pragma("unroll") for (int _i = 0; _i < 2; ++_i) \
;     __builtin_amdgcn_global_load_lds((const unsigned*)((const char*)(gbase) + (voff)[_i]), (LAS unsigned*)(lds + (bufoff) + ldsw + _i * 8192), 16, 0, 0); } while (0)
; #define G_LDA(dst, b, h) do { _Pragma("unroll") for (int m = 0; m < 4; ++m) _Pragma("unroll") for (int k = 0; k < 2; ++k) dst[m][k] = *(const LAS bf16x8*)(lds + G_SA(b, h) + aoff + m * 2048 + k * 1024); } while (0)
; #define G_LDB(dst, b, h) do { _Pragma("unroll") for (int n = 0; n < 2; ++n) _Pragma("unroll") for (int k = 0; k < 2; ++k) dst[n][k] = *(const LAS bf16x8*)(lds + G_SB(b, h) + boff + n * 2048 + k * 1024); } while (0)
; #define G_MMA(ai, bj, At, Bt) do { __builtin_amdgcn_s_setprio(1); _Pragma("unroll") for (int m = 0; m < 4; ++m) _Pragma("unroll") for (int n = 0; n < 2; ++n) _Pragma("unroll") for (int k = 0; k < 2; ++k) \
;     acc[ai][bj][m][n] = __builtin_amdgcn_mfma_f32_16x16x32_bf16(Bt[n][k], At[m][k], acc[ai][bj][m][n], 0, 0, 0); __builtin_amdgcn_s_setprio(0); } while (0)
; #define G_WAIT_V(n) asm volatile("s_waitcnt vmcnt(" #n ")" ::: "memory")
; #define G_WAIT_L(n) asm volatile("s_waitcnt lgkmcnt(" #n ")" ::: "memory")
; #define G_BAR __builtin_amdgcn_s_barrier()
; #define G_SCHED __builtin_amdgcn_sched_barrier(0)
; template <int GP> DI void gemm_phase(const Params& p, int l, int which, char* smem, int wv) {
;     ...
;       G_LDB(B0, 0, 0); G_SCHED; G_LDA(At, 0, 0); G_STAGE(G_SA(1, 1), a1 + hstep, voffA);
;       G_WAIT_L(8); G_BAR; G_WAIT_L(0); G_MMA(0, 0, At, B0); G_BAR; G_SCHED;
;       G_LDB(B1, 0, 1); G_STAGE(G_SB(0, 0), b2, vb0);
;       G_BAR; G_WAIT_L(0); G_MMA(0, 1, At, B1); G_BAR;
;       G_LDA(At, 0, 1); G_STAGE(G_SA(0, 0), a2, voffA);
;       G_BAR; G_WAIT_L(0); G_MMA(1, 0, At, B0); G_BAR; G_SCHED;
;       G_STAGE(G_SB(0, 1), b2, vb1);
;       G_WAIT_V(6); G_BAR; G_MMA(1, 1, At, B1); G_BAR;
.Lkf_top:
	ds_read_b128 v[148:151], v228
	ds_read_b128 v[152:155], v228 offset:1024
	ds_read_b128 v[156:159], v228 offset:2048
	ds_read_b128 v[160:163], v228 offset:3072
	ds_read_b128 v[164:167], v211
	ds_read_b128 v[168:171], v211 offset:1024
	ds_read_b128 v[172:175], v211 offset:2048
	ds_read_b128 v[176:179], v211 offset:3072
	ds_read_b128 v[180:183], v211 offset:4096
	ds_read_b128 v[184:187], v211 offset:5120
	ds_read_b128 v[188:191], v211 offset:6144
	ds_read_b128 v[192:195], v211 offset:7168
	global_load_lds_dwordx4 v138, s[100:101]
	s_add_i32 m0, s23, 0xe000
	s_nop 0
	global_load_lds_dwordx4 v140, s[100:101]
	s_waitcnt lgkmcnt(8)
	s_barrier
	s_waitcnt lgkmcnt(0)
	v_mfma_f32_16x16x32_bf16 v[62:65], v[148:151], v[164:167], v[62:65]
	v_mfma_f32_16x16x32_bf16 v[58:61], v[156:159], v[164:167], v[58:61]
	s_mov_b32 m0, s25
	v_mfma_f32_16x16x32_bf16 v[54:57], v[148:151], v[172:175], v[54:57]
	v_mfma_f32_16x16x32_bf16 v[50:53], v[156:159], v[172:175], v[50:53]
	v_mfma_f32_16x16x32_bf16 v[46:49], v[148:151], v[180:183], v[46:49]
	v_mfma_f32_16x16x32_bf16 v[42:45], v[156:159], v[180:183], v[42:45]
	v_mfma_f32_16x16x32_bf16 v[38:41], v[148:151], v[188:191], v[38:41]
	v_mfma_f32_16x16x32_bf16 v[34:37], v[156:159], v[188:191], v[34:37]
	v_mfma_f32_16x16x32_bf16 v[62:65], v[152:155], v[168:171], v[62:65]
	v_mfma_f32_16x16x32_bf16 v[58:61], v[160:163], v[168:171], v[58:61]
	v_mfma_f32_16x16x32_bf16 v[54:57], v[152:155], v[176:179], v[54:57]
	v_mfma_f32_16x16x32_bf16 v[50:53], v[160:163], v[176:179], v[50:53]
	v_mfma_f32_16x16x32_bf16 v[46:49], v[152:155], v[184:187], v[46:49]
	v_mfma_f32_16x16x32_bf16 v[42:45], v[160:163], v[184:187], v[42:45]
	v_mfma_f32_16x16x32_bf16 v[38:41], v[152:155], v[192:195], v[38:41]
	v_mfma_f32_16x16x32_bf16 v[34:37], v[160:163], v[192:195], v[34:37]
	s_barrier
	ds_read_b128 v[196:199], v228 offset:16384
	ds_read_b128 v[200:203], v228 offset:17408
	ds_read_b128 v[204:207], v228 offset:18432
	ds_read_b128 v[238:241], v228 offset:19456
	global_load_lds_dwordx4 v0, s[6:7]
	s_mov_b32 m0, s58
	s_nop 0
	global_load_lds_dwordx4 v136, s[6:7]
	s_barrier
	s_waitcnt lgkmcnt(0)
	v_mfma_f32_16x16x32_bf16 v[30:33], v[196:199], v[164:167], v[30:33]
	v_mfma_f32_16x16x32_bf16 v[26:29], v[204:207], v[164:167], v[26:29]
	s_mov_b32 m0, s23
	v_mfma_f32_16x16x32_bf16 v[22:25], v[196:199], v[172:175], v[22:25]
	v_mfma_f32_16x16x32_bf16 v[18:21], v[204:207], v[172:175], v[18:21]
	v_mfma_f32_16x16x32_bf16 v[14:17], v[196:199], v[180:183], v[14:17]
	v_mfma_f32_16x16x32_bf16 v[10:13], v[204:207], v[180:183], v[10:13]
	v_mfma_f32_16x16x32_bf16 v[6:9], v[196:199], v[188:191], v[6:9]
	v_mfma_f32_16x16x32_bf16 v[2:5], v[204:207], v[188:191], v[2:5]
	v_mfma_f32_16x16x32_bf16 v[30:33], v[200:203], v[168:171], v[30:33]
	v_mfma_f32_16x16x32_bf16 v[26:29], v[238:241], v[168:171], v[26:29]
	v_mfma_f32_16x16x32_bf16 v[22:25], v[200:203], v[176:179], v[22:25]
	v_mfma_f32_16x16x32_bf16 v[18:21], v[238:241], v[176:179], v[18:21]
	v_mfma_f32_16x16x32_bf16 v[14:17], v[200:203], v[184:187], v[14:17]
	v_mfma_f32_16x16x32_bf16 v[10:13], v[238:241], v[184:187], v[10:13]
	v_mfma_f32_16x16x32_bf16 v[6:9], v[200:203], v[192:195], v[6:9]
	v_mfma_f32_16x16x32_bf16 v[2:5], v[238:241], v[192:195], v[2:5]
	s_barrier
	ds_read_b128 v[164:167], v211 offset:16384
	ds_read_b128 v[168:171], v211 offset:17408
	ds_read_b128 v[172:175], v211 offset:18432
	ds_read_b128 v[176:179], v211 offset:19456
	ds_read_b128 v[180:183], v211 offset:20480
	ds_read_b128 v[184:187], v211 offset:21504
	ds_read_b128 v[188:191], v211 offset:22528
	ds_read_b128 v[192:195], v211 offset:23552
	global_load_lds_dwordx4 v132, s[8:9]
	s_mov_b32 m0, s59
	s_nop 0
	global_load_lds_dwordx4 v134, s[8:9]
	s_barrier
	s_waitcnt lgkmcnt(0)
	v_mfma_f32_16x16x32_bf16 v[66:69], v[148:151], v[164:167], v[66:69]
	v_mfma_f32_16x16x32_bf16 v[70:73], v[156:159], v[164:167], v[70:73]
	s_mov_b32 m0, s60
	v_mfma_f32_16x16x32_bf16 v[74:77], v[148:151], v[172:175], v[74:77]
	v_mfma_f32_16x16x32_bf16 v[78:81], v[156:159], v[172:175], v[78:81]
	v_mfma_f32_16x16x32_bf16 v[82:85], v[148:151], v[180:183], v[82:85]
	v_mfma_f32_16x16x32_bf16 v[86:89], v[156:159], v[180:183], v[86:89]
	v_mfma_f32_16x16x32_bf16 v[90:93], v[148:151], v[188:191], v[90:93]
	v_mfma_f32_16x16x32_bf16 v[94:97], v[156:159], v[188:191], v[94:97]
	v_mfma_f32_16x16x32_bf16 v[66:69], v[152:155], v[168:171], v[66:69]
	v_mfma_f32_16x16x32_bf16 v[70:73], v[160:163], v[168:171], v[70:73]
	v_mfma_f32_16x16x32_bf16 v[74:77], v[152:155], v[176:179], v[74:77]
	v_mfma_f32_16x16x32_bf16 v[78:81], v[160:163], v[176:179], v[78:81]
	v_mfma_f32_16x16x32_bf16 v[82:85], v[152:155], v[184:187], v[82:85]
	v_mfma_f32_16x16x32_bf16 v[86:89], v[160:163], v[184:187], v[86:89]
	v_mfma_f32_16x16x32_bf16 v[90:93], v[152:155], v[192:195], v[90:93]
	v_mfma_f32_16x16x32_bf16 v[94:97], v[160:163], v[192:195], v[94:97]
	s_barrier
	global_load_lds_dwordx4 v130, s[6:7]
	s_mov_b32 m0, s61
	s_nop 0
	global_load_lds_dwordx4 v142, s[6:7]
	s_waitcnt vmcnt(6)
	s_barrier
	v_mfma_f32_16x16x32_bf16 v[98:101], v[196:199], v[164:167], v[98:101]
	v_mfma_f32_16x16x32_bf16 v[102:105], v[204:207], v[164:167], v[102:105]
	s_add_u32 s100, s8, 0x80000
	s_addc_u32 s101, s9, 0
	s_mov_b32 m0, s62
	v_mfma_f32_16x16x32_bf16 v[106:109], v[196:199], v[172:175], v[106:109]
	v_mfma_f32_16x16x32_bf16 v[110:113], v[204:207], v[172:175], v[110:113]
	v_mfma_f32_16x16x32_bf16 v[114:117], v[196:199], v[180:183], v[114:117]
	v_mfma_f32_16x16x32_bf16 v[118:121], v[204:207], v[180:183], v[118:121]
	v_mfma_f32_16x16x32_bf16 v[122:125], v[196:199], v[188:191], v[122:125]
	v_mfma_f32_16x16x32_bf16 v[126:129], v[204:207], v[188:191], v[126:129]
	v_mfma_f32_16x16x32_bf16 v[98:101], v[200:203], v[168:171], v[98:101]
	v_mfma_f32_16x16x32_bf16 v[102:105], v[238:241], v[168:171], v[102:105]
	v_mfma_f32_16x16x32_bf16 v[106:109], v[200:203], v[176:179], v[106:109]
	v_mfma_f32_16x16x32_bf16 v[110:113], v[238:241], v[176:179], v[110:113]
	v_mfma_f32_16x16x32_bf16 v[114:117], v[200:203], v[184:187], v[114:117]
	v_mfma_f32_16x16x32_bf16 v[118:121], v[238:241], v[184:187], v[118:121]
	v_mfma_f32_16x16x32_bf16 v[122:125], v[200:203], v[192:195], v[122:125]
	v_mfma_f32_16x16x32_bf16 v[126:129], v[238:241], v[192:195], v[126:129]
	s_barrier
; #define G_STAGE(bufoff, gbase, voff) do { _Pragma("unroll") for (int _i = 0; _i < 2; ++_i) \
;     __builtin_amdgcn_global_load_lds((const unsigned*)((const char*)(gbase) + (voff)[_i]), (LAS unsigned*)(lds + (bufoff) + ldsw + _i * 8192), 16, 0, 0); } while (0)
; #define G_LDA(dst, b, h) do { _Pragma("unroll") for (int m = 0; m < 4; ++m) _Pragma("unroll") for (int k = 0; k < 2; ++k) dst[m][k] = *(const LAS bf16x8*)(lds + G_SA(b, h) + aoff + m * 2048 + k * 1024); } while (0)
; #define G_LDB(dst, b, h) do { _Pragma("unroll") for (int n = 0; n < 2; ++n) _Pragma("unroll") for (int k = 0; k < 2; ++k) dst[n][k] = *(const LAS bf16x8*)(lds + G_SB(b, h) + boff + n * 2048 + k * 1024); } while (0)
; #define G_MMA(ai, bj, At, Bt) do { __builtin_amdgcn_s_setprio(1); _Pragma("unroll") for (int m = 0; m < 4; ++m) _Pragma("unroll") for (int n = 0; n < 2; ++n) _Pragma("unroll") for (int k = 0; k < 2; ++k) \
;     acc[ai][bj][m][n] = __builtin_amdgcn_mfma_f32_16x16x32_bf16(Bt[n][k], At[m][k], acc[ai][bj][m][n], 0, 0, 0); __builtin_amdgcn_s_setprio(0); } while (0)
; #define G_WAIT_V(n) asm volatile("s_waitcnt vmcnt(" #n ")" ::: "memory")
; #define G_WAIT_L(n) asm volatile("s_waitcnt lgkmcnt(" #n ")" ::: "memory")
; #define G_BAR __builtin_amdgcn_s_barrier()
; #define G_SCHED __builtin_amdgcn_sched_barrier(0)
; template <int GP> DI void gemm_phase(const Params& p, int l, int which, char* smem, int wv) {
;     ...
;       G_LDB(B0, 1, 0); G_SCHED; G_LDA(At, 1, 0); G_STAGE(G_SA(0, 1), a2 + hstep, voffA);
;       G_WAIT_L(8); G_BAR; G_WAIT_L(0); G_MMA(0, 0, At, B0); G_BAR; G_SCHED;
;       G_LDB(B1, 1, 1); G_STAGE(G_SB(1, 0), b3, vb0);
;       G_BAR; G_WAIT_L(0); G_MMA(0, 1, At, B1); G_BAR;
;       G_LDA(At, 1, 1); G_STAGE(G_SA(1, 0), a3, voffA);
;       G_BAR; G_WAIT_L(0); G_MMA(1, 0, At, B0); G_BAR; G_SCHED;
;       G_STAGE(G_SB(1, 1), b3, vb1);
;       G_WAIT_V(6); G_BAR; G_MMA(1, 1, At, B1); G_BAR;
	ds_read_b128 v[148:151], v228 offset:32768
	ds_read_b128 v[152:155], v228 offset:33792
	ds_read_b128 v[156:159], v228 offset:34816
	ds_read_b128 v[160:163], v228 offset:35840
	ds_read_b128 v[164:167], v211 offset:32768
	ds_read_b128 v[168:171], v211 offset:33792
	ds_read_b128 v[172:175], v211 offset:34816
	ds_read_b128 v[176:179], v211 offset:35840
	ds_read_b128 v[180:183], v211 offset:36864
	ds_read_b128 v[184:187], v211 offset:37888
	ds_read_b128 v[188:191], v211 offset:38912
	ds_read_b128 v[192:195], v211 offset:39936
	global_load_lds_dwordx4 v132, s[100:101]
	s_mov_b32 m0, s63
	s_nop 0
	global_load_lds_dwordx4 v134, s[100:101]
	s_waitcnt lgkmcnt(8)
	s_barrier
	s_waitcnt lgkmcnt(0)
	v_mfma_f32_16x16x32_bf16 v[62:65], v[148:151], v[164:167], v[62:65]
	v_mfma_f32_16x16x32_bf16 v[58:61], v[156:159], v[164:167], v[58:61]
	s_mov_b32 m0, s21
	s_add_u32 s100, s6, s16
	s_addc_u32 s101, s7, s17
	v_mfma_f32_16x16x32_bf16 v[54:57], v[148:151], v[172:175], v[54:57]
	v_mfma_f32_16x16x32_bf16 v[50:53], v[156:159], v[172:175], v[50:53]
	v_mfma_f32_16x16x32_bf16 v[46:49], v[148:151], v[180:183], v[46:49]
	v_mfma_f32_16x16x32_bf16 v[42:45], v[156:159], v[180:183], v[42:45]
	v_mfma_f32_16x16x32_bf16 v[38:41], v[148:151], v[188:191], v[38:41]
	v_mfma_f32_16x16x32_bf16 v[34:37], v[156:159], v[188:191], v[34:37]
	v_mfma_f32_16x16x32_bf16 v[62:65], v[152:155], v[168:171], v[62:65]
	v_mfma_f32_16x16x32_bf16 v[58:61], v[160:163], v[168:171], v[58:61]
	v_mfma_f32_16x16x32_bf16 v[54:57], v[152:155], v[176:179], v[54:57]
	v_mfma_f32_16x16x32_bf16 v[50:53], v[160:163], v[176:179], v[50:53]
	v_mfma_f32_16x16x32_bf16 v[46:49], v[152:155], v[184:187], v[46:49]
	v_mfma_f32_16x16x32_bf16 v[42:45], v[160:163], v[184:187], v[42:45]
	v_mfma_f32_16x16x32_bf16 v[38:41], v[152:155], v[192:195], v[38:41]
	v_mfma_f32_16x16x32_bf16 v[34:37], v[160:163], v[192:195], v[34:37]
	s_barrier
	ds_read_b128 v[196:199], v228 offset:49152
	ds_read_b128 v[200:203], v228 offset:50176
	ds_read_b128 v[204:207], v228 offset:51200
	ds_read_b128 v[238:241], v228 offset:52224
	global_load_lds_dwordx4 v0, s[100:101]
	s_mov_b32 m0, s64
	s_nop 0
	global_load_lds_dwordx4 v136, s[100:101]
	s_barrier
	s_waitcnt lgkmcnt(0)
	v_mfma_f32_16x16x32_bf16 v[30:33], v[196:199], v[164:167], v[30:33]
	v_mfma_f32_16x16x32_bf16 v[26:29], v[204:207], v[164:167], v[26:29]
	s_mov_b32 m0, s65
	s_add_u32 s100, s8, s16
	s_addc_u32 s101, s9, s17
	v_mfma_f32_16x16x32_bf16 v[22:25], v[196:199], v[172:175], v[22:25]
	v_mfma_f32_16x16x32_bf16 v[18:21], v[204:207], v[172:175], v[18:21]
	v_mfma_f32_16x16x32_bf16 v[14:17], v[196:199], v[180:183], v[14:17]
	v_mfma_f32_16x16x32_bf16 v[10:13], v[204:207], v[180:183], v[10:13]
	v_mfma_f32_16x16x32_bf16 v[6:9], v[196:199], v[188:191], v[6:9]
	v_mfma_f32_16x16x32_bf16 v[2:5], v[204:207], v[188:191], v[2:5]
	v_mfma_f32_16x16x32_bf16 v[30:33], v[200:203], v[168:171], v[30:33]
	v_mfma_f32_16x16x32_bf16 v[26:29], v[238:241], v[168:171], v[26:29]
	v_mfma_f32_16x16x32_bf16 v[22:25], v[200:203], v[176:179], v[22:25]
	v_mfma_f32_16x16x32_bf16 v[18:21], v[238:241], v[176:179], v[18:21]
	v_mfma_f32_16x16x32_bf16 v[14:17], v[200:203], v[184:187], v[14:17]
	v_mfma_f32_16x16x32_bf16 v[10:13], v[238:241], v[184:187], v[10:13]
	v_mfma_f32_16x16x32_bf16 v[6:9], v[200:203], v[192:195], v[6:9]
	v_mfma_f32_16x16x32_bf16 v[2:5], v[238:241], v[192:195], v[2:5]
	s_barrier
	ds_read_b128 v[164:167], v211 offset:49152
	ds_read_b128 v[168:171], v211 offset:50176
	ds_read_b128 v[172:175], v211 offset:51200
	ds_read_b128 v[176:179], v211 offset:52224
	ds_read_b128 v[180:183], v211 offset:53248
	ds_read_b128 v[184:187], v211 offset:54272
	ds_read_b128 v[188:191], v211 offset:55296
	ds_read_b128 v[192:195], v211 offset:56320
	global_load_lds_dwordx4 v132, s[100:101]
	s_mov_b32 m0, s66
	s_nop 0
	global_load_lds_dwordx4 v134, s[100:101]
	s_barrier
	s_waitcnt lgkmcnt(0)
	v_mfma_f32_16x16x32_bf16 v[66:69], v[148:151], v[164:167], v[66:69]
	v_mfma_f32_16x16x32_bf16 v[70:73], v[156:159], v[164:167], v[70:73]
	s_mov_b32 m0, s67
	s_add_u32 s100, s6, s16
	s_addc_u32 s101, s7, s17
	v_mfma_f32_16x16x32_bf16 v[74:77], v[148:151], v[172:175], v[74:77]
	v_mfma_f32_16x16x32_bf16 v[78:81], v[156:159], v[172:175], v[78:81]
	v_mfma_f32_16x16x32_bf16 v[82:85], v[148:151], v[180:183], v[82:85]
	v_mfma_f32_16x16x32_bf16 v[86:89], v[156:159], v[180:183], v[86:89]
	v_mfma_f32_16x16x32_bf16 v[90:93], v[148:151], v[188:191], v[90:93]
	v_mfma_f32_16x16x32_bf16 v[94:97], v[156:159], v[188:191], v[94:97]
	v_mfma_f32_16x16x32_bf16 v[66:69], v[152:155], v[168:171], v[66:69]
	v_mfma_f32_16x16x32_bf16 v[70:73], v[160:163], v[168:171], v[70:73]
	v_mfma_f32_16x16x32_bf16 v[74:77], v[152:155], v[176:179], v[74:77]
	v_mfma_f32_16x16x32_bf16 v[78:81], v[160:163], v[176:179], v[78:81]
	v_mfma_f32_16x16x32_bf16 v[82:85], v[152:155], v[184:187], v[82:85]
	v_mfma_f32_16x16x32_bf16 v[86:89], v[160:163], v[184:187], v[86:89]
	v_mfma_f32_16x16x32_bf16 v[90:93], v[152:155], v[192:195], v[90:93]
	v_mfma_f32_16x16x32_bf16 v[94:97], v[160:163], v[192:195], v[94:97]
	s_barrier
	global_load_lds_dwordx4 v130, s[100:101]
	s_mov_b32 m0, s68
	s_nop 0
	global_load_lds_dwordx4 v142, s[100:101]
	s_waitcnt vmcnt(6)
	s_barrier
	v_mfma_f32_16x16x32_bf16 v[98:101], v[196:199], v[164:167], v[98:101]
	v_mfma_f32_16x16x32_bf16 v[102:105], v[204:207], v[164:167], v[102:105]
	s_add_i32 m0, s23, 0xc000
	v_mfma_f32_16x16x32_bf16 v[106:109], v[196:199], v[172:175], v[106:109]
	v_mfma_f32_16x16x32_bf16 v[110:113], v[204:207], v[172:175], v[110:113]
	v_mfma_f32_16x16x32_bf16 v[114:117], v[196:199], v[180:183], v[114:117]
	v_mfma_f32_16x16x32_bf16 v[118:121], v[204:207], v[180:183], v[118:121]
	v_mfma_f32_16x16x32_bf16 v[122:125], v[196:199], v[188:191], v[122:125]
	v_mfma_f32_16x16x32_bf16 v[126:129], v[204:207], v[188:191], v[126:129]
	v_mfma_f32_16x16x32_bf16 v[98:101], v[200:203], v[168:171], v[98:101]
	s_add_i32 s50, s50, 2
	s_add_u32 s2, s2, 0x100
	s_addc_u32 s3, s3, 0
	v_mfma_f32_16x16x32_bf16 v[102:105], v[238:241], v[168:171], v[102:105]
	s_add_u32 s8, s28, s2
	s_addc_u32 s9, s29, s3
	v_mfma_f32_16x16x32_bf16 v[106:109], v[200:203], v[176:179], v[106:109]
	s_add_u32 s100, s8, 0x80080
	s_addc_u32 s101, s9, 0
	v_mfma_f32_16x16x32_bf16 v[110:113], v[238:241], v[176:179], v[110:113]
	s_add_u32 s8, s8, 0x100
	s_addc_u32 s9, s9, 0
	v_mfma_f32_16x16x32_bf16 v[114:117], v[200:203], v[184:187], v[114:117]
	s_add_u32 s6, s74, s2
	s_addc_u32 s7, s75, s3
	v_mfma_f32_16x16x32_bf16 v[118:121], v[238:241], v[184:187], v[118:121]
	v_mfma_f32_16x16x32_bf16 v[122:125], v[200:203], v[192:195], v[122:125]
	v_mfma_f32_16x16x32_bf16 v[126:129], v[238:241], v[192:195], v[126:129]
	s_cmp_gt_u32 s50, 29
	s_barrier
	s_cbranch_scc1 .LBB0_219
	s_cmpk_lg_i32 s2, 0xf00
	s_cbranch_scc1 .Lkf_top
